# overlap v15: v4 with the recurrence polling its row-group counter one chunk ahead and without the L1 invalidate (first-touch, write-through rows)
# baseline (speedup 1.0000x reference)
.Lhs_chk_g0:
	s_waitcnt vmcnt(0)
	v_readfirstlane_b32 s100, v254
	s_cmp_ge_u32 s100, 0xc0
	s_cbranch_scc1 .Lhs_join_g0
	s_sleep 24
	s_add_u32 s99, s99, 1
	s_cmp_lt_u32 s99, 0x2000
	s_cbranch_scc1 .Lhs_g0
